# in-proj unit to column-tile mapping permuted so every workgroup's three units hold exactly one rope-type tile (was: some workgroups got two Q_B tiles)
# baseline (speedup 1.0000x reference)
;     DI bool next(int i, Unit& u) const {
;         const long L = (long)i * G + c; if (L >= nwg) return false;
;         u.kt0 = 0; u.nkt = nkt;
;         int wgid = (int)L; { const int q = nwg / NXCD, r = nwg % NXCD, xcd = wgid % NXCD, off = wgid / NXCD; wgid = (xcd < r ? xcd * (q + 1) : r * (q + 1) + (xcd - r) * q) + off; }
;         const int nig = WGM * nN, gid = wgid / nig, fm = gid * WGM, gsz = (nM - fm) < WGM ? (nM - fm) : WGM;
;         u.pm = fm + ((wgid % nig) % gsz); u.pn = (wgid % nig) / gsz; return true;
.LBB0_91:
	s_cmp_lt_i32 s38, 2
	s_cselect_b64 s[0:1], -1, 0
	s_waitcnt lgkmcnt(0)
	s_and_b64 s[14:15], s[0:1], s[4:5]
	s_andn2_b64 vcc, exec, s[14:15]
	s_cbranch_vccnz .LBB0_547
	v_readlane_b32 s4, v253, 1
	s_cmpk_lt_i32 s2, 0x288
	v_readlane_b32 s5, v253, 2
	s_cselect_b64 s[0:1], -1, 0
	s_cmpk_gt_i32 s2, 0x287
	v_readfirstlane_b32 s12, v226
	s_cbranch_scc1 .LBB0_95
	s_ashr_i32 s6, s2, 31
	s_lshr_b32 s6, s6, 29
	s_add_i32 s6, s2, s6
	s_ashr_i32 s7, s6, 3
	s_and_b32 s6, s6, -8
	s_sub_i32 s6, s2, s6
	s_cmp_lt_i32 s6, 0
	s_movk_i32 s8, 0x52
	s_cselect_b32 s8, s8, 0x51
	s_mul_i32 s6, s6, s8
	s_add_i32 s6, s6, s7
	s_mul_hi_i32 s7, s6, 0x38e38e39
	s_lshr_b32 s8, s7, 31
	s_ashr_i32 s7, s7, 4
	s_add_i32 s7, s7, s8
	s_lshl_b32 s8, s7, 3
	s_mulk_i32 s7, 0x48
	s_sub_i32 s6, s6, s7
	s_bfe_i32 s7, s6, 0x80000
	s_bfe_u32 s7, s7, 0x3000c
	s_add_i32 s7, s6, s7
	s_bfe_i32 s9, s7, 0x80000
	s_and_b32 s7, s7, 0xf8
	s_sub_i32 s6, s6, s7
	s_sext_i32_i16 s9, s9
	s_sext_i32_i8 s6, s6
	s_add_i32 s10, s8, s6
	s_ashr_i32 s6, s9, 3
	s_lshl_b32 s7, s6, 2
	s_mov_b32 s8, 0x28157046
	s_mov_b32 s9, 3
	s_lshr_b64 s[8:9], s[8:9], s7
	s_and_b32 s6, s8, 15
	v_lshrrev_b32_e32 v153, 2, v226
	s_andn2_b64 vcc, exec, s[0:1]
	v_lshlrev_b32_e32 v145, 2, v226
	s_cbranch_vccz .LBB0_96

;     DI bool next(int i, Unit& u) const {
;         const long L = (long)i * G + c; if (L >= nwg) return false;
;         u.kt0 = 0; u.nkt = nkt;
;         int wgid = (int)L; { const int q = nwg / NXCD, r = nwg % NXCD, xcd = wgid % NXCD, off = wgid / NXCD; wgid = (xcd < r ? xcd * (q + 1) : r * (q + 1) + (xcd - r) * q) + off; }
;         const int nig = WGM * nN, gid = wgid / nig, fm = gid * WGM, gsz = (nM - fm) < WGM ? (nM - fm) : WGM;
;         u.pm = fm + ((wgid % nig) % gsz); u.pn = (wgid % nig) / gsz; return true;
.LBB0_101:
	s_add_i32 s89, s89, 1
	v_readlane_b32 s7, v253, 0
	s_mul_i32 s4, s89, s72
	s_mul_hi_u32 s5, s89, s7
	s_add_i32 s5, s5, s4
	s_mul_i32 s4, s89, s7
	s_add_u32 s34, s4, s2
	s_addc_u32 s35, s5, s73
	v_cmp_gt_i64_e32 vcc, s[34:35], v[180:181]
	v_cmp_lt_i64_e64 s[4:5], s[34:35], v[178:179]
	s_cbranch_vccnz .LBB0_103
	s_ashr_i32 s7, s34, 31
	s_lshr_b32 s7, s7, 29
	s_add_i32 s7, s34, s7
	s_ashr_i32 s11, s7, 3
	s_and_b32 s7, s7, -8
	s_sub_i32 s7, s34, s7
	s_cmp_lt_i32 s7, 0
	s_cselect_b32 s18, s74, 0x51
	s_mul_i32 s7, s7, s18
	s_add_i32 s7, s7, s11
	s_mul_hi_i32 s11, s7, 0x38e38e39
	s_lshr_b32 s18, s11, 31
	s_ashr_i32 s11, s11, 4
	s_add_i32 s11, s11, s18
	s_lshl_b32 s18, s11, 3
	s_sub_i32 s28, 0x48, s18
	s_min_i32 s29, s28, 8
	s_abs_i32 s28, s29
	v_cvt_f32_u32_e32 v0, s28
	s_sub_i32 s31, 0, s28
	s_mulk_i32 s11, 0x48
	s_sub_i32 s7, s7, s11
	v_rcp_iflag_f32_e32 v0, v0
	s_abs_i32 s11, s7
	s_xor_b32 s30, s7, s29
	s_ashr_i32 s30, s30, 31
	v_mul_f32_e32 v0, 0x4f7ffffe, v0
	v_cvt_u32_f32_e32 v0, v0
	s_nop 0
	v_readfirstlane_b32 s34, v0
	s_mul_i32 s31, s31, s34
	s_mul_hi_u32 s31, s34, s31
	s_add_i32 s34, s34, s31
	s_mul_hi_u32 s31, s11, s34
	s_mul_i32 s34, s31, s28
	s_sub_i32 s11, s11, s34
	s_add_i32 s35, s31, 1
	s_sub_i32 s34, s11, s28
	s_cmp_ge_u32 s11, s28
	s_cselect_b32 s31, s35, s31
	s_cselect_b32 s11, s34, s11
	s_add_i32 s34, s31, 1
	s_cmp_ge_u32 s11, s28
	s_cselect_b32 s11, s34, s31
	s_xor_b32 s11, s11, s30
	s_sub_i32 s28, s11, s30
	s_mul_i32 s11, s28, s29
	s_sub_i32 s7, s7, s11
	s_add_i32 s30, s18, s7
	s_lshl_b32 s31, s28, 2
	s_mov_b32 s34, 0x28157046
	s_mov_b32 s35, 3
	s_lshr_b64 s[34:35], s[34:35], s31
	s_and_b32 s28, s34, 15
